# combined + pooling window-sum loops rotated (next trip's LDS reads in flight during accumulation)
# speedup vs baseline: 1.0056x; 1.0056x over previous
; #define LAS __attribute__((address_space(3)))
; DEV unsigned pk2(float lo, float hi) { unsigned r; asm("v_cvt_pk_bf16_f32 %0, %1, %2" : "=v"(r) : "v"(lo), "v"(hi)); return r; }
; DEV void pool_phase(const Fr& F, int l, int it0, int stride) {
;     ...
;         { const int t = tid >> 2, part = tid & 3; const int p = p0 + t; const int lo = max(p - half, 0), hi = min(p + win - half, seqlen); const float rc = 1.f / (float)(hi - lo);
;           float s[16];
; #pragma unroll
;           for (int j = 0; j < 16; ++j) s[j] = 0.f;
;           for (int o = -half; o < half; ++o) {
; #pragma unroll
;               for (int j = 0; j < 16; ++j) s[j] += Zt[(t + 8 + o) * 64 + part * 16 + j]; }
; #pragma unroll
;           for (int j = 0; j < 16; j += 2) { const float a0 = s[j] * rc - Zt[(t + 8) * 64 + part * 16 + j], a1 = s[j + 1] * rc - Zt[(t + 8) * 64 + part * 16 + j + 1];
;               *(LAS unsigned*)(Dm + t * 72 + part * 16 + j) = pk2(a0, a1); } }
;         __syncthreads();
;         f32x4 acc[4];
; #pragma unroll
;         for (int nt = 0; nt < 4; ++nt) { acc[nt] = (f32x4){0.f, 0.f, 0.f, 0.f};
; #pragma unroll
;             for (int k0 = 0; k0 < 64; k0 += 32) { const bf16x8 xf = *(const LAS bf16x8*)(Dm + (16 * w + fr) * 72 + k0 + fq * 8); const bf16x8 yf = tr_frag(Wp, 72, k0, 16 * nt, F.lane);
;                 acc[nt] = __builtin_amdgcn_mfma_f32_16x16x32_bf16(yf, xf, acc[nt], 0, 0, 0); } }
;         { const int t = 16 * w + fr;
; #pragma unroll
;           for (int nt = 0; nt < 4; ++nt) { const int d0 = 16 * nt + 4 * fq; const f32x4 ps = *(const f32x4*)(F.in[I_POOLS] + l * 256 + g * 64 + d0);
;               u32x2 wv; wv.x = pk2(acc[nt][0] * ps[0], acc[nt][1] * ps[1]); wv.y = pk2(acc[nt][2] * ps[2], acc[nt][3] * ps[3]);
;               *(u32x2*)(F.MIX + (size_t)(row0 + t) * D + 768 + g * 64 + d0) = wv; } }
.LBB0_496:
	ds_read_b128 v[18:21], v1
	ds_read_b128 v[22:25], v1 offset:16
	ds_read_b128 v[26:29], v1 offset:32
	ds_read_b128 v[30:33], v1 offset:48
	s_add_i32 s58, s58, 1
	v_add_u32_e32 v1, 0x100, v1
	s_cmp_ge_i32 s58, s7
	s_cbranch_scc1 .Lpp_epi_s3
.Lpp_loop_s3:
	s_waitcnt lgkmcnt(3)
	v_pk_add_f32 v[16:17], v[16:17], v[18:19]
	v_pk_add_f32 v[14:15], v[14:15], v[20:21]
	ds_read_b128 v[18:21], v1
	s_waitcnt lgkmcnt(3)
	v_pk_add_f32 v[12:13], v[12:13], v[22:23]
	v_pk_add_f32 v[10:11], v[10:11], v[24:25]
	ds_read_b128 v[22:25], v1 offset:16
	s_waitcnt lgkmcnt(3)
	v_pk_add_f32 v[8:9], v[8:9], v[26:27]
	v_pk_add_f32 v[6:7], v[6:7], v[28:29]
	ds_read_b128 v[26:29], v1 offset:32
	s_waitcnt lgkmcnt(3)
	v_pk_add_f32 v[4:5], v[4:5], v[30:31]
	v_pk_add_f32 v[2:3], v[2:3], v[32:33]
	ds_read_b128 v[30:33], v1 offset:48
	s_add_i32 s58, s58, 1
	v_add_u32_e32 v1, 0x100, v1
	s_cmp_ge_i32 s58, s7
	s_cbranch_scc0 .Lpp_loop_s3
.Lpp_epi_s3:
	s_waitcnt lgkmcnt(3)
	v_pk_add_f32 v[16:17], v[16:17], v[18:19]
	v_pk_add_f32 v[14:15], v[14:15], v[20:21]
	s_waitcnt lgkmcnt(2)
	v_pk_add_f32 v[12:13], v[12:13], v[22:23]
	v_pk_add_f32 v[10:11], v[10:11], v[24:25]
	s_waitcnt lgkmcnt(1)
	v_pk_add_f32 v[8:9], v[8:9], v[26:27]
	v_pk_add_f32 v[6:7], v[6:7], v[28:29]
	s_waitcnt lgkmcnt(0)
	v_pk_add_f32 v[4:5], v[4:5], v[30:31]
	v_pk_add_f32 v[2:3], v[2:3], v[32:33]
	v_add_u32_e32 v1, s57, v185
	v_subrev_u32_e32 v18, s7, v1
	v_add_u32_e32 v1, s6, v1
	v_subrev_u32_e32 v1, s7, v1
	v_max_i32_e32 v18, 0, v18
	v_min_i32_e32 v1, s56, v1
	v_sub_u32_e32 v1, v1, v18
	v_cvt_f32_i32_e32 v1, v1
	v_add_u32_e32 v30, 0x800, v186
	s_add_i32 s44, s44, s45
	s_lshl_b32 s60, s41, 8
	v_div_scale_f32 v18, s[6:7], v1, v1, 1.0
	v_rcp_f32_e32 v19, v18
	v_readlane_b32 s6, v239, 25
	v_readlane_b32 s7, v239, 26
	v_mov_b32_e32 v169, v0
	v_fma_f32 v20, -v18, v19, 1.0
	v_fmac_f32_e32 v19, v20, v19
	v_div_scale_f32 v20, vcc, 1.0, v1, 1.0
	v_mul_f32_e32 v21, v20, v19
	v_fma_f32 v22, -v18, v21, v20
	v_fmac_f32_e32 v21, v22, v19
	v_fma_f32 v18, -v18, v21, v20
	v_div_fmas_f32 v18, v18, v19, v21
	v_div_fixup_f32 v1, v18, v1, 1.0
	ds_read2_b64 v[18:21], v30 offset1:1
	ds_read2_b64 v[22:25], v30 offset0:2 offset1:3
	ds_read2_b64 v[26:29], v30 offset0:4 offset1:5
	ds_read2_b64 v[30:33], v30 offset0:6 offset1:7
	s_waitcnt lgkmcnt(3)
	v_fma_f32 v16, v1, v16, -v18
	v_fma_f32 v17, v1, v17, -v19
	v_fma_f32 v14, v1, v14, -v20
	v_fma_f32 v15, v1, v15, -v21
	s_waitcnt lgkmcnt(2)
	v_fma_f32 v12, v1, v12, -v22
	v_fma_f32 v13, v1, v13, -v23
	v_fma_f32 v10, v1, v10, -v24
	v_fma_f32 v11, v1, v11, -v25
	s_waitcnt lgkmcnt(1)
	v_fma_f32 v8, v1, v8, -v26
	v_fma_f32 v9, v1, v9, -v27
	v_fma_f32 v6, v1, v6, -v28
	v_fma_f32 v7, v1, v7, -v29
	s_waitcnt lgkmcnt(0)
	v_fma_f32 v4, v1, v4, -v30
	v_fma_f32 v5, v1, v5, -v31
	v_fma_f32 v2, v1, v2, -v32
	v_fma_f32 v1, v1, v3, -v33
	v_cvt_pk_bf16_f32 v14, v14, v15
	v_add_u32_e32 v15, 0x9000, v212
	v_cvt_pk_bf16_f32 v1, v2, v1
	v_cvt_pk_bf16_f32 v16, v16, v17
	v_cvt_pk_bf16_f32 v12, v12, v13
	v_cvt_pk_bf16_f32 v10, v10, v11
	v_cvt_pk_bf16_f32 v8, v8, v9
	v_cvt_pk_bf16_f32 v6, v6, v7
	v_cvt_pk_bf16_f32 v4, v4, v5
	ds_write2_b32 v15, v4, v1 offset0:6 offset1:7
	v_add_u32_e32 v1, v201, v202
	ds_write2_b32 v15, v16, v14 offset1:1
	ds_write2_b32 v15, v12, v10 offset0:2 offset1:3
	ds_write2_b32 v15, v8, v6 offset0:4 offset1:5
	s_waitcnt lgkmcnt(0)
	s_barrier
	ds_read_b128 v[2:5], v213 offset:36864
	ds_read_b64_tr_b16 v[8:9], v1 offset:55872
	ds_read_b64_tr_b16 v[6:7], v1 offset:55296
	ds_read_b64_tr_b16 v[10:11], v1 offset:55328
	ds_read_b128 v[14:17], v213 offset:36928
	ds_read_b64_tr_b16 v[18:19], v1 offset:59904
	ds_read_b64_tr_b16 v[20:21], v1 offset:60480
	ds_read_b64_tr_b16 v[12:13], v1 offset:55904
	s_waitcnt lgkmcnt(5)
	v_mfma_f32_16x16x32_bf16 v[6:9], v[6:9], v[2:5], 0
	s_waitcnt lgkmcnt(1)
	v_mfma_f32_16x16x32_bf16 v[18:21], v[18:21], v[14:17], v[6:9]
	s_waitcnt lgkmcnt(0)
	v_mfma_f32_16x16x32_bf16 v[6:9], v[10:13], v[2:5], 0
	ds_read_b64_tr_b16 v[10:11], v1 offset:59936
	ds_read_b64_tr_b16 v[12:13], v1 offset:60512
	s_waitcnt lgkmcnt(0)
	v_mfma_f32_16x16x32_bf16 v[10:13], v[10:13], v[14:17], v[6:9]
	s_nop 3
	ds_read_b64_tr_b16 v[6:7], v1 offset:55360
	ds_read_b64_tr_b16 v[8:9], v1 offset:55936
	ds_read_b64_tr_b16 v[22:23], v1 offset:59968
	ds_read_b64_tr_b16 v[24:25], v1 offset:60544
	s_waitcnt lgkmcnt(2)
	v_mfma_f32_16x16x32_bf16 v[6:9], v[6:9], v[2:5], 0
	s_waitcnt lgkmcnt(0)
	v_mfma_f32_16x16x32_bf16 v[6:9], v[22:25], v[14:17], v[6:9]
	ds_read_b64_tr_b16 v[22:23], v1 offset:55392
	ds_read_b64_tr_b16 v[24:25], v1 offset:55968
	s_waitcnt lgkmcnt(0)
	v_mfma_f32_16x16x32_bf16 v[2:5], v[22:25], v[2:5], 0
	ds_read_b64_tr_b16 v[22:23], v1 offset:60000
	ds_read_b64_tr_b16 v[24:25], v1 offset:60576
	s_waitcnt lgkmcnt(0)
	v_mfma_f32_16x16x32_bf16 v[2:5], v[22:25], v[14:17], v[2:5]
	v_add_u32_e32 v14, s44, v187
	v_ashrrev_i32_e32 v15, 31, v14
	v_lshl_add_u64 v[24:25], v[164:165], 0, s[60:61]
	v_lshlrev_b64 v[22:23], 11, v[14:15]
	global_load_dwordx4 v[14:17], v[24:25], off
	global_load_dwordx4 v[244:247], v[24:25], off offset:64
	global_load_dwordx4 v[248:251], v[24:25], off offset:128
	global_load_dwordx4 v[252:255], v[24:25], off offset:192
	s_lshl_b32 s60, s41, 7
	s_waitcnt vmcnt(0)
	v_mul_f32_e32 v1, v18, v14
	v_mul_f32_e32 v14, v19, v15
	v_cvt_pk_bf16_f32 v14, v1, v14
	v_mul_f32_e32 v1, v20, v16
	v_mul_f32_e32 v15, v21, v17
	v_lshl_add_u64 v[16:17], s[6:7], 0, v[22:23]
	v_lshl_add_u64 v[16:17], v[16:17], 0, s[60:61]
	v_lshl_add_u64 v[18:19], v[16:17], 0, v[168:169]
	v_cvt_pk_bf16_f32 v15, v1, v15
	global_store_dwordx2 v[18:19], v[14:15], off offset:1536
	s_mov_b64 s[6:7], -1
	v_mul_f32_e32 v1, v10, v244
	v_mul_f32_e32 v10, v11, v245
	v_mul_f32_e32 v11, v13, v247
	v_cvt_pk_bf16_f32 v10, v1, v10
	v_mul_f32_e32 v1, v12, v246
	v_cvt_pk_bf16_f32 v11, v1, v11
	global_store_dwordx2 v[18:19], v[10:11], off offset:1568
	v_mul_f32_e32 v1, v6, v248
	v_mul_f32_e32 v6, v7, v249
	v_mul_f32_e32 v7, v9, v251
	v_cvt_pk_bf16_f32 v6, v1, v6
	v_mul_f32_e32 v1, v8, v250
	v_cvt_pk_bf16_f32 v7, v1, v7
	global_store_dwordx2 v[18:19], v[6:7], off offset:1600
	v_mul_f32_e32 v1, v2, v252
	v_mul_f32_e32 v2, v3, v253
	v_mul_f32_e32 v3, v5, v255
	v_cvt_pk_bf16_f32 v2, v1, v2
	v_mul_f32_e32 v1, v4, v254
	v_cvt_pk_bf16_f32 v3, v1, v3
	global_store_dwordx2 v[18:19], v[2:3], off offset:1632
	s_barrier
	s_branch .LBB0_499

; #define LAS __attribute__((address_space(3)))
; DEV unsigned pk2(float lo, float hi) { unsigned r; asm("v_cvt_pk_bf16_f32 %0, %1, %2" : "=v"(r) : "v"(lo), "v"(hi)); return r; }
; DEV void pool_phase(const Fr& F, int l, int it0, int stride) {
;     ...
;         { const int t = tid >> 2, part = tid & 3; const int p = p0 + t; const int lo = max(p - half, 0), hi = min(p + win - half, seqlen); const float rc = 1.f / (float)(hi - lo);
;           float s[16];
; #pragma unroll
;           for (int j = 0; j < 16; ++j) s[j] = 0.f;
;           for (int o = -half; o < half; ++o) {
; #pragma unroll
;               for (int j = 0; j < 16; ++j) s[j] += Zt[(t + 8 + o) * 64 + part * 16 + j]; }
; #pragma unroll
;           for (int j = 0; j < 16; j += 2) { const float a0 = s[j] * rc - Zt[(t + 8) * 64 + part * 16 + j], a1 = s[j + 1] * rc - Zt[(t + 8) * 64 + part * 16 + j + 1];
;               *(LAS unsigned*)(Dm + t * 72 + part * 16 + j) = pk2(a0, a1); } }
;         __syncthreads();
;         f32x4 acc[4];
; #pragma unroll
;         for (int nt = 0; nt < 4; ++nt) { acc[nt] = (f32x4){0.f, 0.f, 0.f, 0.f};
; #pragma unroll
;             for (int k0 = 0; k0 < 64; k0 += 32) { const bf16x8 xf = *(const LAS bf16x8*)(Dm + (16 * w + fr) * 72 + k0 + fq * 8); const bf16x8 yf = tr_frag(Wp, 72, k0, 16 * nt, F.lane);
;                 acc[nt] = __builtin_amdgcn_mfma_f32_16x16x32_bf16(yf, xf, acc[nt], 0, 0, 0); } }
;         { const int t = 16 * w + fr;
; #pragma unroll
;           for (int nt = 0; nt < 4; ++nt) { const int d0 = 16 * nt + 4 * fq; const f32x4 ps = *(const f32x4*)(F.in[I_POOLS] + l * 256 + g * 64 + d0);
;               u32x2 wv; wv.x = pk2(acc[nt][0] * ps[0], acc[nt][1] * ps[1]); wv.y = pk2(acc[nt][2] * ps[2], acc[nt][3] * ps[3]);
;               *(u32x2*)(F.MIX + (size_t)(row0 + t) * D + 768 + g * 64 + d0) = wv; } }
.LBB0_923:
	ds_read_b128 v[54:57], v27
	ds_read_b128 v[58:61], v27 offset:16
	ds_read_b128 v[62:65], v27 offset:32
	ds_read_b128 v[66:69], v27 offset:48
	s_add_i32 s6, s6, 1
	v_add_u32_e32 v27, 0x100, v27
	s_cmp_ge_i32 s6, s20
	s_cbranch_scc1 .Lpp_epi_s4
.Lpp_loop_s4:
	s_waitcnt lgkmcnt(3)
	v_pk_add_f32 v[38:39], v[38:39], v[54:55]
	v_pk_add_f32 v[36:37], v[36:37], v[56:57]
	ds_read_b128 v[54:57], v27
	s_waitcnt lgkmcnt(3)
	v_pk_add_f32 v[24:25], v[24:25], v[58:59]
	v_pk_add_f32 v[22:23], v[22:23], v[60:61]
	ds_read_b128 v[58:61], v27 offset:16
	s_waitcnt lgkmcnt(3)
	v_pk_add_f32 v[20:21], v[20:21], v[62:63]
	v_pk_add_f32 v[18:19], v[18:19], v[64:65]
	ds_read_b128 v[62:65], v27 offset:32
	s_waitcnt lgkmcnt(3)
	v_pk_add_f32 v[16:17], v[16:17], v[66:67]
	v_pk_add_f32 v[14:15], v[14:15], v[68:69]
	ds_read_b128 v[66:69], v27 offset:48
	s_add_i32 s6, s6, 1
	v_add_u32_e32 v27, 0x100, v27
	s_cmp_ge_i32 s6, s20
	s_cbranch_scc0 .Lpp_loop_s4
.Lpp_epi_s4:
	s_waitcnt lgkmcnt(3)
	v_pk_add_f32 v[38:39], v[38:39], v[54:55]
	v_pk_add_f32 v[36:37], v[36:37], v[56:57]
	s_waitcnt lgkmcnt(2)
	v_pk_add_f32 v[24:25], v[24:25], v[58:59]
	v_pk_add_f32 v[22:23], v[22:23], v[60:61]
	s_waitcnt lgkmcnt(1)
	v_pk_add_f32 v[20:21], v[20:21], v[62:63]
	v_pk_add_f32 v[18:19], v[18:19], v[64:65]
	s_waitcnt lgkmcnt(0)
	v_pk_add_f32 v[16:17], v[16:17], v[66:67]
	v_pk_add_f32 v[14:15], v[14:15], v[68:69]
	s_ashr_i32 s6, s19, 2
	s_mul_hi_i32 s21, s6, 0x7e07e07f
	s_lshr_b32 s22, s21, 31
	s_ashr_i32 s21, s21, 6
	s_add_i32 s21, s21, s22
	s_mulk_i32 s21, 0x82
	s_sub_i32 s21, s6, s21
	s_lshl_b32 s6, s21, 7
	s_add_i32 s22, s6, 0xffffff00
	s_cmp_lt_i32 s21, 2
	s_cselect_b32 s22, s6, s22
	v_add_u32_e32 v27, s22, v42
	s_movk_i32 s21, 0x4000
	v_subrev_u32_e32 v35, s20, v27
	v_add_u32_e32 v27, s7, v27
	s_cselect_b32 s21, 0x100, s21
	v_subrev_u32_e32 v27, s20, v27
	v_max_i32_e32 v35, 0, v35
	v_min_i32_e32 v27, s21, v27
	v_sub_u32_e32 v27, v27, v35
	v_cvt_f32_i32_e32 v27, v27
	s_mul_hi_i32 s7, s19, 0x7e07e07f
	s_lshr_b32 s19, s7, 31
	s_lshr_b32 s7, s7, 8
	v_div_scale_f32 v35, s[20:21], v27, v27, 1.0
	v_rcp_f32_e32 v54, v35
	s_add_i32 s7, s7, s19
	s_mulk_i32 s7, 0x4100
	s_add_i32 s6, s6, s7
	v_fma_f32 v55, -v35, v54, 1.0
	v_fmac_f32_e32 v54, v55, v54
	v_div_scale_f32 v55, vcc, 1.0, v27, 1.0
	v_mul_f32_e32 v56, v55, v54
	v_fma_f32 v57, -v35, v56, v55
	v_fmac_f32_e32 v56, v57, v54
	v_fma_f32 v35, -v35, v56, v55
	v_div_fmas_f32 v35, v35, v54, v56
	v_div_fixup_f32 v27, v35, v27, 1.0
	v_add_u32_e32 v35, 0x800, v43
	ds_read2_b64 v[54:57], v35 offset1:1
	ds_read2_b64 v[58:61], v35 offset0:2 offset1:3
	ds_read2_b64 v[62:65], v35 offset0:4 offset1:5
	ds_read2_b64 v[66:69], v35 offset0:6 offset1:7
	s_lshl_b32 s60, s15, 6
	s_waitcnt lgkmcnt(3)
	v_fma_f32 v36, v27, v36, -v56
	v_fma_f32 v37, v27, v37, -v57
	s_waitcnt lgkmcnt(2)
	v_fma_f32 v24, v27, v24, -v58
	v_fma_f32 v22, v27, v22, -v60
	s_waitcnt lgkmcnt(1)
	v_fma_f32 v20, v27, v20, -v62
	v_fma_f32 v18, v27, v18, -v64
	s_waitcnt lgkmcnt(0)
	v_fma_f32 v16, v27, v16, -v66
	v_fma_f32 v14, v27, v14, -v68
	v_fma_f32 v35, v27, v38, -v54
	v_fma_f32 v38, v27, v39, -v55
	v_cvt_pk_bf16_f32 v36, v36, v37
	v_add_u32_e32 v37, 0x9000, v51
	v_fma_f32 v25, v27, v25, -v59
	v_cvt_pk_bf16_f32 v24, v24, v25
	v_fma_f32 v23, v27, v23, -v61
	v_cvt_pk_bf16_f32 v22, v22, v23
	v_fma_f32 v21, v27, v21, -v63
	v_cvt_pk_bf16_f32 v20, v20, v21
	v_fma_f32 v19, v27, v19, -v65
	v_cvt_pk_bf16_f32 v18, v18, v19
	v_fma_f32 v17, v27, v17, -v67
	v_cvt_pk_bf16_f32 v16, v16, v17
	v_fma_f32 v15, v27, v15, -v69
	v_cvt_pk_bf16_f32 v14, v14, v15
	v_cvt_pk_bf16_f32 v35, v35, v38
	ds_write2_b32 v37, v35, v36 offset1:1
	ds_write2_b32 v37, v24, v22 offset0:2 offset1:3
	ds_write2_b32 v37, v20, v18 offset0:4 offset1:5
	ds_write2_b32 v37, v16, v14 offset0:6 offset1:7
	s_waitcnt lgkmcnt(0)
	s_barrier
	ds_read_b128 v[14:17], v52 offset:36864
	ds_read_b64_tr_b16 v[20:21], v53 offset:55872
	ds_read_b64_tr_b16 v[18:19], v53 offset:55296
	ds_read_b64_tr_b16 v[22:23], v53 offset:55328
	ds_read_b128 v[36:39], v52 offset:36928
	ds_read_b64_tr_b16 v[54:55], v53 offset:59904
	ds_read_b64_tr_b16 v[56:57], v53 offset:60480
	ds_read_b64_tr_b16 v[24:25], v53 offset:55904
	s_waitcnt lgkmcnt(5)
	v_mfma_f32_16x16x32_bf16 v[18:21], v[18:21], v[14:17], 0
	s_and_b64 vcc, exec, s[16:17]
	s_mov_b32 s19, s18
	s_waitcnt lgkmcnt(1)
	v_mfma_f32_16x16x32_bf16 v[54:57], v[54:57], v[36:39], v[18:21]
	s_waitcnt lgkmcnt(0)
	v_mfma_f32_16x16x32_bf16 v[18:21], v[22:25], v[14:17], 0
	ds_read_b64_tr_b16 v[22:23], v53 offset:59936
	ds_read_b64_tr_b16 v[24:25], v53 offset:60512
	s_waitcnt lgkmcnt(0)
	v_mfma_f32_16x16x32_bf16 v[22:25], v[22:25], v[36:39], v[18:21]
	s_nop 3
	ds_read_b64_tr_b16 v[18:19], v53 offset:55360
	ds_read_b64_tr_b16 v[20:21], v53 offset:55936
	ds_read_b64_tr_b16 v[58:59], v53 offset:59968
	ds_read_b64_tr_b16 v[60:61], v53 offset:60544
	s_waitcnt lgkmcnt(2)
	v_mfma_f32_16x16x32_bf16 v[18:21], v[18:21], v[14:17], 0
	s_waitcnt lgkmcnt(0)
	v_mfma_f32_16x16x32_bf16 v[18:21], v[58:61], v[36:39], v[18:21]
	ds_read_b64_tr_b16 v[58:59], v53 offset:55392
	ds_read_b64_tr_b16 v[60:61], v53 offset:55968
	s_waitcnt lgkmcnt(0)
	v_mfma_f32_16x16x32_bf16 v[14:17], v[58:61], v[14:17], 0
	ds_read_b64_tr_b16 v[58:59], v53 offset:60000
	ds_read_b64_tr_b16 v[60:61], v53 offset:60576
	s_waitcnt lgkmcnt(0)
	v_mfma_f32_16x16x32_bf16 v[14:17], v[58:61], v[36:39], v[14:17]
	v_add_u32_e32 v36, s6, v44
	v_ashrrev_i32_e32 v37, 31, v36
	v_lshlrev_b64 v[38:39], 11, v[36:37]
	v_lshl_add_u64 v[36:37], s[60:61], 2, v[32:33]
	global_load_dwordx4 v[58:61], v[36:37], off
	global_load_dwordx4 v[244:247], v[36:37], off offset:64
	global_load_dwordx4 v[248:251], v[36:37], off offset:128
	global_load_dwordx4 v[252:255], v[36:37], off offset:192
	v_lshl_add_u64 v[38:39], s[80:81], 0, v[38:39]
	s_lshl_b32 s60, s15, 7
	v_lshl_add_u64 v[38:39], v[38:39], 0, s[60:61]
	s_waitcnt vmcnt(0)
	v_mul_f32_e32 v35, v55, v59
	v_mul_f32_e32 v27, v54, v58
	v_cvt_pk_bf16_f32 v54, v27, v35
	v_mul_f32_e32 v35, v57, v61
	v_mul_f32_e32 v27, v56, v60
	v_cvt_pk_bf16_f32 v55, v27, v35
	v_mov_b32_e32 v35, v0
	v_lshl_add_u64 v[38:39], v[38:39], 0, v[34:35]
	global_store_dwordx2 v[38:39], v[54:55], off offset:1536
	v_mul_f32_e32 v22, v22, v244
	v_mul_f32_e32 v23, v23, v245
	v_cvt_pk_bf16_f32 v22, v22, v23
	v_mul_f32_e32 v23, v24, v246
	v_mul_f32_e32 v24, v25, v247
	v_cvt_pk_bf16_f32 v23, v23, v24
	global_store_dwordx2 v[38:39], v[22:23], off offset:1568
	v_mul_f32_e32 v18, v18, v248
	v_mul_f32_e32 v19, v19, v249
	v_cvt_pk_bf16_f32 v18, v18, v19
	v_mul_f32_e32 v19, v20, v250
	v_mul_f32_e32 v20, v21, v251
	v_cvt_pk_bf16_f32 v19, v19, v20
	global_store_dwordx2 v[38:39], v[18:19], off offset:1600
	v_mul_f32_e32 v14, v14, v252
	v_mul_f32_e32 v15, v15, v253
	v_cvt_pk_bf16_f32 v14, v14, v15
	v_mul_f32_e32 v15, v16, v254
	v_mul_f32_e32 v16, v17, v255
	v_cvt_pk_bf16_f32 v15, v15, v16
	global_store_dwordx2 v[38:39], v[14:15], off offset:1632
	s_barrier
	s_cbranch_vccz .LBB0_902
